# grid barrier: acquire invalidate issued when the workgroup's own XCD has completed (not while same-XCD stragglers still use the L2)
# speedup vs baseline: 1.0182x; 1.0015x over previous
.LBB0_166:
	s_or_b64 exec, exec, s[4:5]
	s_mov_b32 s100, 0
	v_readlane_b32 s98, v255, 37
	v_cvt_f32_u32_e32 v4, v0
	s_waitcnt vmcnt(0)
	v_readfirstlane_b32 s4, v3
	s_mov_b32 s20, 1
	v_rcp_iflag_f32_e32 v4, v4
	v_add_u32_e32 v1, s4, v1
	v_mul_f32_e32 v3, 0x4f7ffffe, v4
	v_cvt_u32_f32_e32 v3, v3
	v_sub_u32_e32 v4, 0, v0
	v_mul_lo_u32 v4, v4, v3
	v_mul_hi_u32 v4, v3, v4
	v_add_u32_e32 v3, v3, v4
	v_mul_hi_u32 v3, v1, v3
	v_mul_lo_u32 v4, v3, v0
	v_sub_u32_e32 v4, v1, v4
	v_add_u32_e32 v5, 1, v3
	v_cmp_ge_u32_e32 vcc, v4, v0
	v_add_u32_e32 v1, 1, v1
	s_nop 0
	v_cndmask_b32_e32 v3, v3, v5, vcc
	v_sub_u32_e32 v5, v4, v0
	v_cndmask_b32_e32 v4, v4, v5, vcc
	v_add_u32_e32 v5, 1, v3
	v_cmp_ge_u32_e32 vcc, v4, v0
	s_nop 1
	v_cndmask_b32_e32 v3, v3, v5, vcc
	v_add_u32_e32 v3, 1, v3
	v_mul_lo_u32 v0, v3, v0
	v_cmp_eq_u32_e32 vcc, v1, v0
	s_and_saveexec_b64 s[4:5], vcc
	s_cbranch_execz .LBB0_168
	v_readlane_b32 s6, v255, 37
	s_lshl_b32 s6, s6, 2
	v_readlane_b32 s8, v255, 35
	buffer_wbl2 sc1
	s_waitcnt lgkmcnt(0)
	s_waitcnt vmcnt(0)
	v_readlane_b32 s9, v255, 36
	s_add_u32 s6, s8, s6
	s_addc_u32 s7, s9, 0
	v_mov_b32_e32 v0, 0x3000
	global_store_dword v0, v3, s[6:7] offset:1024 sc1

.LBB0_171:
	global_load_dwordx4 v[6:9], v[0:1], off sc1
	global_load_dwordx4 v[10:13], v[0:1], off offset:16 sc1
	global_load_dwordx4 v[14:17], v[0:1], off offset:32 sc1
	global_load_dwordx4 v[18:21], v[0:1], off offset:48 sc1
	s_waitcnt vmcnt(0)
	s_or_b64 s[10:11], s[10:11], exec
	v_sub_u32_e32 v9, v9, v3
	v_sub_u32_e32 v5, v6, v3
	v_lshrrev_b32_e32 v9, 28, v9
	v_sub_u32_e32 v13, v13, v3
	v_sub_u32_e32 v17, v17, v3
	v_sub_u32_e32 v6, v10, v3
	v_sub_u32_e32 v10, v14, v3
	v_lshrrev_b32_e32 v5, 31, v5
	v_sub_u32_e32 v14, v18, v3
	v_sub_u32_e32 v18, v19, v3
	v_sub_u32_e32 v8, v8, v3
	v_sub_u32_e32 v12, v12, v3
	v_sub_u32_e32 v19, v20, v3
	v_and_b32_e32 v9, 8, v9
	v_and_b32_sdwa v13, v13, s21 dst_sel:DWORD dst_unused:UNUSED_PAD src0_sel:BYTE_3 src1_sel:DWORD
	v_lshrrev_b32_e32 v17, 20, v17
	v_sub_u32_e32 v20, v21, v3
	v_lshrrev_b32_e32 v8, 29, v8
	v_lshrrev_b32_e32 v12, 25, v12
	v_sub_u32_e32 v16, v16, v3
	v_and_b32_e32 v17, 0x800, v17
	v_and_b32_sdwa v20, v20, s22 dst_sel:DWORD dst_unused:UNUSED_PAD src0_sel:WORD_1 src1_sel:DWORD
	v_or3_b32 v5, v13, v5, v9
	v_sub_u32_e32 v7, v7, v3
	v_sub_u32_e32 v11, v11, v3
	v_and_b32_e32 v8, 4, v8
	v_and_b32_e32 v12, 64, v12
	v_lshrrev_b32_e32 v16, 21, v16
	v_lshrrev_b32_e32 v19, 17, v19
	v_or3_b32 v5, v5, v17, v20
	v_lshrrev_b32_e32 v7, 30, v7
	v_lshrrev_b32_e32 v11, 26, v11
	v_sub_u32_e32 v15, v15, v3
	v_and_b32_e32 v16, 0x400, v16
	v_and_b32_e32 v19, 0x4000, v19
	v_or3_b32 v5, v5, v12, v8
	v_and_b32_e32 v7, 2, v7
	v_and_b32_e32 v11, 32, v11
	v_lshrrev_b32_e32 v15, 22, v15
	v_lshrrev_b32_e32 v18, 18, v18
	v_or3_b32 v5, v5, v16, v19
	v_lshrrev_b32_e32 v6, 27, v6
	v_lshrrev_b32_e32 v10, 23, v10
	v_and_b32_e32 v15, 0x200, v15
	v_and_b32_e32 v18, 0x2000, v18
	v_or3_b32 v5, v5, v11, v7
	v_and_b32_e32 v6, 16, v6
	v_and_b32_e32 v10, 0x100, v10
	v_lshrrev_b32_e32 v14, 19, v14
	v_or3_b32 v5, v5, v15, v18
	v_and_b32_e32 v14, 0x1000, v14
	v_or3_b32 v5, v5, v6, v10
	s_waitcnt lgkmcnt(0)
	v_bitop3_b32 v5, v5, v2, v14 bitop3:0xc8
	s_nop 0
	v_readfirstlane_b32 s99, v5
	s_lshr_b32 s99, s99, s98
	s_and_b32 s99, s99, 1
	s_or_b32 s99, s99, s100
	s_cmp_lg_u32 s99, 0
	s_cbranch_scc1 .Lxinv_skip_1
	buffer_inv sc1
	s_mov_b32 s100, 1
.Lxinv_skip_1:
	v_cmp_ne_u32_e32 vcc, 0, v5
	s_or_b64 s[8:9], s[8:9], exec
	s_and_saveexec_b64 s[12:13], vcc
	s_cbranch_execz .LBB0_170
	s_and_b32 s16, s20, 0xff
	s_mov_b64 s[14:15], -1
	s_cmp_eq_u32 s16, 0
	s_mov_b64 s[16:17], -1
	s_mov_b64 s[18:19], -1
	s_cbranch_scc1 .LBB0_175
	s_and_b64 vcc, exec, s[18:19]
	s_cbranch_vccz .LBB0_169

.LBB0_182:
	s_or_b64 exec, exec, s[4:5]
	s_cmp_lg_u32 s100, 0
	s_cbranch_scc1 .Lxinv_done_1
	buffer_inv sc1
.Lxinv_done_1:
	s_waitcnt vmcnt(0)
.LBB0_183:
	s_or_b64 exec, exec, s[2:3]
	s_barrier

.Lxinv_done_2:
	s_waitcnt vmcnt(0)
.LBB0_1366:
	s_or_b64 exec, exec, s[2:3]
	s_barrier

.Lxinv_done_3:
	s_waitcnt vmcnt(0)
.LBB0_1670:
	s_or_b64 exec, exec, s[0:1]
	s_barrier

.Lxinv_done_4:
	s_waitcnt vmcnt(0)
.LBB0_1833:
	s_or_b64 exec, exec, s[0:1]
	s_barrier

.Lxinv_done_5:
	s_waitcnt vmcnt(0)
.LBB0_2272:
	s_or_b64 exec, exec, s[0:1]
	s_barrier

.LBB0_2342:
	s_or_b64 exec, exec, s[2:3]
	s_mov_b32 s100, 0
	v_readlane_b32 s98, v255, 37
	v_cvt_f32_u32_e32 v4, v0
	s_waitcnt vmcnt(0)
	v_readfirstlane_b32 s2, v3
	s_mov_b32 s18, 1
	v_rcp_iflag_f32_e32 v4, v4
	v_add_u32_e32 v1, s2, v1
	v_mul_f32_e32 v3, 0x4f7ffffe, v4
	v_cvt_u32_f32_e32 v3, v3
	v_sub_u32_e32 v4, 0, v0
	v_mul_lo_u32 v4, v4, v3
	v_mul_hi_u32 v4, v3, v4
	v_add_u32_e32 v3, v3, v4
	v_mul_hi_u32 v3, v1, v3
	v_mul_lo_u32 v4, v3, v0
	v_sub_u32_e32 v4, v1, v4
	v_add_u32_e32 v5, 1, v3
	v_cmp_ge_u32_e32 vcc, v4, v0
	v_add_u32_e32 v1, 1, v1
	s_nop 0
	v_cndmask_b32_e32 v3, v3, v5, vcc
	v_sub_u32_e32 v5, v4, v0
	v_cndmask_b32_e32 v4, v4, v5, vcc
	v_add_u32_e32 v5, 1, v3
	v_cmp_ge_u32_e32 vcc, v4, v0
	s_nop 1
	v_cndmask_b32_e32 v3, v3, v5, vcc
	v_add_u32_e32 v3, 1, v3
	v_mul_lo_u32 v0, v3, v0
	v_cmp_eq_u32_e32 vcc, v1, v0
	s_and_saveexec_b64 s[2:3], vcc
	s_cbranch_execz .LBB0_2344
	v_readlane_b32 s4, v255, 37
	s_lshl_b32 s4, s4, 2
	v_readlane_b32 s6, v255, 35
	buffer_wbl2 sc1
	s_waitcnt lgkmcnt(0)
	s_waitcnt vmcnt(0)
	v_readlane_b32 s7, v255, 36
	s_add_u32 s4, s6, s4
	s_addc_u32 s5, s7, 0
	v_mov_b32_e32 v0, 0x3000
	global_store_dword v0, v3, s[4:5] offset:1024 sc1

.LBB0_2347:
	global_load_dwordx4 v[6:9], v[0:1], off sc1
	global_load_dwordx4 v[10:13], v[0:1], off offset:16 sc1
	global_load_dwordx4 v[14:17], v[0:1], off offset:32 sc1
	global_load_dwordx4 v[18:21], v[0:1], off offset:48 sc1
	s_waitcnt vmcnt(0)
	s_or_b64 s[8:9], s[8:9], exec
	v_sub_u32_e32 v9, v9, v3
	v_sub_u32_e32 v5, v6, v3
	v_lshrrev_b32_e32 v9, 28, v9
	v_sub_u32_e32 v13, v13, v3
	v_sub_u32_e32 v17, v17, v3
	v_sub_u32_e32 v6, v10, v3
	v_sub_u32_e32 v10, v14, v3
	v_lshrrev_b32_e32 v5, 31, v5
	v_sub_u32_e32 v14, v18, v3
	v_sub_u32_e32 v18, v19, v3
	v_sub_u32_e32 v8, v8, v3
	v_sub_u32_e32 v12, v12, v3
	v_sub_u32_e32 v19, v20, v3
	v_and_b32_e32 v9, 8, v9
	v_and_b32_sdwa v13, v13, s19 dst_sel:DWORD dst_unused:UNUSED_PAD src0_sel:BYTE_3 src1_sel:DWORD
	v_lshrrev_b32_e32 v17, 20, v17
	v_sub_u32_e32 v20, v21, v3
	v_lshrrev_b32_e32 v8, 29, v8
	v_lshrrev_b32_e32 v12, 25, v12
	v_sub_u32_e32 v16, v16, v3
	v_and_b32_e32 v17, 0x800, v17
	v_and_b32_sdwa v20, v20, s20 dst_sel:DWORD dst_unused:UNUSED_PAD src0_sel:WORD_1 src1_sel:DWORD
	v_or3_b32 v5, v13, v5, v9
	v_sub_u32_e32 v7, v7, v3
	v_sub_u32_e32 v11, v11, v3
	v_and_b32_e32 v8, 4, v8
	v_and_b32_e32 v12, 64, v12
	v_lshrrev_b32_e32 v16, 21, v16
	v_lshrrev_b32_e32 v19, 17, v19
	v_or3_b32 v5, v5, v17, v20
	v_lshrrev_b32_e32 v7, 30, v7
	v_lshrrev_b32_e32 v11, 26, v11
	v_sub_u32_e32 v15, v15, v3
	v_and_b32_e32 v16, 0x400, v16
	v_and_b32_e32 v19, 0x4000, v19
	v_or3_b32 v5, v5, v12, v8
	v_and_b32_e32 v7, 2, v7
	v_and_b32_e32 v11, 32, v11
	v_lshrrev_b32_e32 v15, 22, v15
	v_lshrrev_b32_e32 v18, 18, v18
	v_or3_b32 v5, v5, v16, v19
	v_lshrrev_b32_e32 v6, 27, v6
	v_lshrrev_b32_e32 v10, 23, v10
	v_and_b32_e32 v15, 0x200, v15
	v_and_b32_e32 v18, 0x2000, v18
	v_or3_b32 v5, v5, v11, v7
	v_and_b32_e32 v6, 16, v6
	v_and_b32_e32 v10, 0x100, v10
	v_lshrrev_b32_e32 v14, 19, v14
	v_or3_b32 v5, v5, v15, v18
	v_and_b32_e32 v14, 0x1000, v14
	v_or3_b32 v5, v5, v6, v10
	s_waitcnt lgkmcnt(0)
	v_bitop3_b32 v5, v5, v2, v14 bitop3:0xc8
	s_nop 0
	v_readfirstlane_b32 s99, v5
	s_lshr_b32 s99, s99, s98
	s_and_b32 s99, s99, 1
	s_or_b32 s99, s99, s100
	s_cmp_lg_u32 s99, 0
	s_cbranch_scc1 .Lxinv_skip_6
	buffer_inv sc1
	s_mov_b32 s100, 1
.Lxinv_skip_6:
	v_cmp_ne_u32_e32 vcc, 0, v5
	s_or_b64 s[6:7], s[6:7], exec
	s_and_saveexec_b64 s[10:11], vcc
	s_cbranch_execz .LBB0_2346
	s_and_b32 s14, s18, 0xff
	s_mov_b64 s[12:13], -1
	s_cmp_eq_u32 s14, 0
	s_mov_b64 s[14:15], -1
	s_mov_b64 s[16:17], -1
	s_cbranch_scc1 .LBB0_2351
	s_and_b64 vcc, exec, s[16:17]
	s_cbranch_vccz .LBB0_2345

.LBB0_2358:
	s_or_b64 exec, exec, s[2:3]
	s_cmp_lg_u32 s100, 0
	s_cbranch_scc1 .Lxinv_done_6
	buffer_inv sc1
.Lxinv_done_6:
	s_waitcnt vmcnt(0)
.LBB0_2359:
	s_or_b64 exec, exec, s[0:1]
	s_barrier

.Lxinv_done_7:
	s_waitcnt vmcnt(0)
.LBB0_2425:
	s_or_b64 exec, exec, s[0:1]
	s_barrier

.Lxinv_done_8:
	s_waitcnt vmcnt(0)
.LBB0_2560:
	s_or_b64 exec, exec, s[0:1]
	s_barrier

.Lxinv_done_9:
	s_waitcnt vmcnt(0)
.LBB0_2961:
	s_or_b64 exec, exec, s[2:3]
	s_barrier

.Lxinv_done_10:
	s_waitcnt vmcnt(0)
.LBB0_3048:
	s_or_b64 exec, exec, s[0:1]
	s_barrier

.Lxinv_done_11:
	s_waitcnt vmcnt(0)
.LBB0_3102:
	s_or_b64 exec, exec, s[0:1]
	s_barrier

	.amdhsa_kernel _Z10fwd_kernel4Args
		.amdhsa_group_segment_fixed_size 0
		.amdhsa_private_segment_fixed_size 0
		.amdhsa_kernarg_size 592
		.amdhsa_user_sgpr_count 2
		.amdhsa_user_sgpr_dispatch_ptr 0
		.amdhsa_user_sgpr_queue_ptr 0
		.amdhsa_user_sgpr_kernarg_segment_ptr 1
		.amdhsa_user_sgpr_dispatch_id 0
		.amdhsa_user_sgpr_kernarg_preload_length 0
		.amdhsa_user_sgpr_kernarg_preload_offset 0
		.amdhsa_user_sgpr_private_segment_size 0
		.amdhsa_uses_dynamic_stack 0
		.amdhsa_enable_private_segment 0
		.amdhsa_system_sgpr_workgroup_id_x 1
		.amdhsa_system_sgpr_workgroup_id_y 0
		.amdhsa_system_sgpr_workgroup_id_z 0
		.amdhsa_system_sgpr_workgroup_info 0
		.amdhsa_system_vgpr_workitem_id 0
		.amdhsa_next_free_vgpr 256
		.amdhsa_next_free_sgpr 101
		.amdhsa_accum_offset 256
		.amdhsa_reserve_vcc 1
		.amdhsa_float_round_mode_32 0
		.amdhsa_float_round_mode_16_64 0
		.amdhsa_float_denorm_mode_32 3
		.amdhsa_float_denorm_mode_16_64 3
		.amdhsa_dx10_clamp 1
		.amdhsa_ieee_mode 1
		.amdhsa_fp16_overflow 0
		.amdhsa_tg_split 0
		.amdhsa_exception_fp_ieee_invalid_op 0
		.amdhsa_exception_fp_denorm_src 0
		.amdhsa_exception_fp_ieee_div_zero 0
		.amdhsa_exception_fp_ieee_overflow 0
		.amdhsa_exception_fp_ieee_underflow 0
		.amdhsa_exception_fp_ieee_inexact 0
		.amdhsa_exception_int_div_zero 0
	.end_amdhsa_kernel

amdhsa.kernels:
  - .agpr_count:     0
    .args:
      - .offset:         0
        .size:           336
        .value_kind:     by_value
      - .offset:         336
        .size:           4
        .value_kind:     hidden_block_count_x
      - .offset:         340
        .size:           4
        .value_kind:     hidden_block_count_y
      - .offset:         344
        .size:           4
        .value_kind:     hidden_block_count_z
      - .offset:         348
        .size:           2
        .value_kind:     hidden_group_size_x
      - .offset:         350
        .size:           2
        .value_kind:     hidden_group_size_y
      - .offset:         352
        .size:           2
        .value_kind:     hidden_group_size_z
      - .offset:         354
        .size:           2
        .value_kind:     hidden_remainder_x
      - .offset:         356
        .size:           2
        .value_kind:     hidden_remainder_y
      - .offset:         358
        .size:           2
        .value_kind:     hidden_remainder_z
      - .offset:         376
        .size:           8
        .value_kind:     hidden_global_offset_x
      - .offset:         384
        .size:           8
        .value_kind:     hidden_global_offset_y
      - .offset:         392
        .size:           8
        .value_kind:     hidden_global_offset_z
      - .offset:         400
        .size:           2
        .value_kind:     hidden_grid_dims
      - .offset:         456
        .size:           4
        .value_kind:     hidden_dynamic_lds_size
    .group_segment_fixed_size: 0
    .kernarg_segment_align: 8
    .kernarg_segment_size: 592
    .language:       OpenCL C
    .language_version:
      - 2
      - 0
    .max_flat_workgroup_size: 512
    .name:           _Z10fwd_kernel4Args
    .private_segment_fixed_size: 0
    .sgpr_count:     107
    .sgpr_spill_count: 133
    .symbol:         _Z10fwd_kernel4Args.kd
    .uniform_work_group_size: 1
    .uses_dynamic_stack: false
    .vgpr_count:     256
    .vgpr_spill_count: 0
    .wavefront_size: 64
